# phase A: compact epilogue for plain column tiles with permlane-swapped dwordx4 stores
# speedup vs baseline: 1.0454x; 1.0098x over previous
; __device__ __forceinline__ void phaseA(const Params& p, int layer) {
;     ...
; #pragma unroll
;       for (int ai = 0; ai < 2; ai++)
; #pragma unroll
;         for (int m = 0; m < 4; m++) {
;           __builtin_amdgcn_sched_barrier(0);
;           const int tok = brow + ai * 128 + wr * 64 + m * 16 + fr_o;
; #pragma unroll
;           for (int bj = 0; bj < 2; bj++)
; #pragma unroll
;             for (int n = 0; n < 2; n++) {
;               const int cb = bcol + bj * 128 + wc * 32 + n * 16;
;               f32x4 v = acc[ai][bj][m][n];
;               if (n == 0 && (wc & 1) == 0 && ((cb >= C_ATQ && cb < C_ATV) || (cb >= C_IDQ && cb < C_IDW))) {
;                 f32x4 cs = *(const f32x4*)(p.CS + (size_t)tok * 16 + 4 * (fq & 1));
;                 f32x4 sn = *(const f32x4*)(p.CS + (size_t)tok * 16 + 8 + 4 * (fq & 1));
; #pragma unroll
;                 for (int e = 0; e < 4; e++) {
;                   float o = __shfl_xor(v[e], 32);
;                   v[e] = (fq < 2) ? (v[e] * cs[e] - o * sn[e]) : (v[e] * cs[e] + o * sn[e]);
;                 }
;               }
;               const int nn = cb + fq * 4;
;               if (nn < 5716) {
;                 const int dn = nn + (nn >= 2628 ? 12 : 0);
;                 uint2 pv = make_uint2(pk2(v[0], v[1]), pk2(v[2], v[3]));
;                 *(uint2*)(p.P + (size_t)tok * PW + dn) = pv;
.Lepa_fast0:
	v_readlane_b32 s62, v253, 13
	v_readlane_b32 s63, v253, 14
	v_mul_u32_u24_e32 v128, 0x2d00, v154
	v_lshl_add_u32 v129, v130, 1, s20
	v_lshl_add_u32 v128, v129, 1, v128
	v_cvt_pk_bf16_f32 v124, v124, v125
	v_cvt_pk_bf16_f32 v125, v126, v127
	v_cvt_pk_bf16_f32 v126, v120, v121
	v_cvt_pk_bf16_f32 v127, v122, v123
	v_cvt_pk_bf16_f32 v116, v116, v117
	v_cvt_pk_bf16_f32 v117, v118, v119
	v_cvt_pk_bf16_f32 v118, v112, v113
	v_cvt_pk_bf16_f32 v119, v114, v115
	s_nop 1
	v_permlane32_swap_b32_e32 v124, v126
	v_permlane32_swap_b32_e32 v125, v127
	v_permlane32_swap_b32_e32 v116, v118
	v_permlane32_swap_b32_e32 v117, v119
	s_nop 1
	v_permlane16_swap_b32_e32 v124, v126
	v_permlane16_swap_b32_e32 v125, v127
	v_permlane16_swap_b32_e32 v116, v118
	v_permlane16_swap_b32_e32 v117, v119
	global_store_dwordx4 v128, v[124:127], s[62:63]
	global_store_dwordx4 v128, v[116:119], s[62:63] offset:256
	v_add_u32_e32 v129, 0x2d000, v128
	v_cvt_pk_bf16_f32 v108, v108, v109
	v_cvt_pk_bf16_f32 v109, v110, v111
	v_cvt_pk_bf16_f32 v110, v104, v105
	v_cvt_pk_bf16_f32 v111, v106, v107
	v_cvt_pk_bf16_f32 v100, v100, v101
	v_cvt_pk_bf16_f32 v101, v102, v103
	v_cvt_pk_bf16_f32 v102, v96, v97
	v_cvt_pk_bf16_f32 v103, v98, v99
	s_nop 1
	v_permlane32_swap_b32_e32 v108, v110
	v_permlane32_swap_b32_e32 v109, v111
	v_permlane32_swap_b32_e32 v100, v102
	v_permlane32_swap_b32_e32 v101, v103
	s_nop 1
	v_permlane16_swap_b32_e32 v108, v110
	v_permlane16_swap_b32_e32 v109, v111
	v_permlane16_swap_b32_e32 v100, v102
	v_permlane16_swap_b32_e32 v101, v103
	global_store_dwordx4 v129, v[108:111], s[62:63]
	global_store_dwordx4 v129, v[100:103], s[62:63] offset:256
	v_add_u32_e32 v129, 0x5a000, v128
	v_cvt_pk_bf16_f32 v92, v92, v93
	v_cvt_pk_bf16_f32 v93, v94, v95
	v_cvt_pk_bf16_f32 v94, v88, v89
	v_cvt_pk_bf16_f32 v95, v90, v91
	v_cvt_pk_bf16_f32 v84, v84, v85
	v_cvt_pk_bf16_f32 v85, v86, v87
	v_cvt_pk_bf16_f32 v86, v80, v81
	v_cvt_pk_bf16_f32 v87, v82, v83
	s_nop 1
	v_permlane32_swap_b32_e32 v92, v94
	v_permlane32_swap_b32_e32 v93, v95
	v_permlane32_swap_b32_e32 v84, v86
	v_permlane32_swap_b32_e32 v85, v87
	s_nop 1
	v_permlane16_swap_b32_e32 v92, v94
	v_permlane16_swap_b32_e32 v93, v95
	v_permlane16_swap_b32_e32 v84, v86
	v_permlane16_swap_b32_e32 v85, v87
	global_store_dwordx4 v129, v[92:95], s[62:63]
	global_store_dwordx4 v129, v[84:87], s[62:63] offset:256
	v_add_u32_e32 v129, 0x87000, v128
	v_cvt_pk_bf16_f32 v76, v76, v77
	v_cvt_pk_bf16_f32 v77, v78, v79
	v_cvt_pk_bf16_f32 v78, v72, v73
	v_cvt_pk_bf16_f32 v79, v74, v75
	v_cvt_pk_bf16_f32 v68, v68, v69
	v_cvt_pk_bf16_f32 v69, v70, v71
	v_cvt_pk_bf16_f32 v70, v64, v65
	v_cvt_pk_bf16_f32 v71, v66, v67
	s_nop 1
	v_permlane32_swap_b32_e32 v76, v78
	v_permlane32_swap_b32_e32 v77, v79
	v_permlane32_swap_b32_e32 v68, v70
	v_permlane32_swap_b32_e32 v69, v71
	s_nop 1
	v_permlane16_swap_b32_e32 v76, v78
	v_permlane16_swap_b32_e32 v77, v79
	v_permlane16_swap_b32_e32 v68, v70
	v_permlane16_swap_b32_e32 v69, v71
	global_store_dwordx4 v129, v[76:79], s[62:63]
	global_store_dwordx4 v129, v[68:71], s[62:63] offset:256
	v_add_u32_e32 v129, 0x168000, v128
	v_cvt_pk_bf16_f32 v60, v60, v61
	v_cvt_pk_bf16_f32 v61, v62, v63
	v_cvt_pk_bf16_f32 v62, v56, v57
	v_cvt_pk_bf16_f32 v63, v58, v59
	v_cvt_pk_bf16_f32 v52, v52, v53
	v_cvt_pk_bf16_f32 v53, v54, v55
	v_cvt_pk_bf16_f32 v54, v48, v49
	v_cvt_pk_bf16_f32 v55, v50, v51
	s_nop 1
	v_permlane32_swap_b32_e32 v60, v62
	v_permlane32_swap_b32_e32 v61, v63
	v_permlane32_swap_b32_e32 v52, v54
	v_permlane32_swap_b32_e32 v53, v55
	s_nop 1
	v_permlane16_swap_b32_e32 v60, v62
	v_permlane16_swap_b32_e32 v61, v63
	v_permlane16_swap_b32_e32 v52, v54
	v_permlane16_swap_b32_e32 v53, v55
	global_store_dwordx4 v129, v[60:63], s[62:63]
	global_store_dwordx4 v129, v[52:55], s[62:63] offset:256
	v_add_u32_e32 v129, 0x195000, v128
	v_cvt_pk_bf16_f32 v44, v44, v45
	v_cvt_pk_bf16_f32 v45, v46, v47
	v_cvt_pk_bf16_f32 v46, v40, v41
	v_cvt_pk_bf16_f32 v47, v42, v43
	v_cvt_pk_bf16_f32 v36, v36, v37
	v_cvt_pk_bf16_f32 v37, v38, v39
	v_cvt_pk_bf16_f32 v38, v32, v33
	v_cvt_pk_bf16_f32 v39, v34, v35
	s_nop 1
	v_permlane32_swap_b32_e32 v44, v46
	v_permlane32_swap_b32_e32 v45, v47
	v_permlane32_swap_b32_e32 v36, v38
	v_permlane32_swap_b32_e32 v37, v39
	s_nop 1
	v_permlane16_swap_b32_e32 v44, v46
	v_permlane16_swap_b32_e32 v45, v47
	v_permlane16_swap_b32_e32 v36, v38
	v_permlane16_swap_b32_e32 v37, v39
	global_store_dwordx4 v129, v[44:47], s[62:63]
	global_store_dwordx4 v129, v[36:39], s[62:63] offset:256
	v_add_u32_e32 v129, 0x1c2000, v128
	v_cvt_pk_bf16_f32 v28, v28, v29
	v_cvt_pk_bf16_f32 v29, v30, v31
	v_cvt_pk_bf16_f32 v30, v24, v25
	v_cvt_pk_bf16_f32 v31, v26, v27
	v_cvt_pk_bf16_f32 v20, v20, v21
	v_cvt_pk_bf16_f32 v21, v22, v23
	v_cvt_pk_bf16_f32 v22, v16, v17
	v_cvt_pk_bf16_f32 v23, v18, v19
	s_nop 1
	v_permlane32_swap_b32_e32 v28, v30
	v_permlane32_swap_b32_e32 v29, v31
	v_permlane32_swap_b32_e32 v20, v22
	v_permlane32_swap_b32_e32 v21, v23
	s_nop 1
	v_permlane16_swap_b32_e32 v28, v30
	v_permlane16_swap_b32_e32 v29, v31
	v_permlane16_swap_b32_e32 v20, v22
	v_permlane16_swap_b32_e32 v21, v23
	global_store_dwordx4 v129, v[28:31], s[62:63]
	global_store_dwordx4 v129, v[20:23], s[62:63] offset:256
	v_add_u32_e32 v129, 0x1ef000, v128
	v_cvt_pk_bf16_f32 v12, v12, v13
	v_cvt_pk_bf16_f32 v13, v14, v15
	v_cvt_pk_bf16_f32 v14, v8, v9
	v_cvt_pk_bf16_f32 v15, v10, v11
	v_cvt_pk_bf16_f32 v4, v4, v5
	v_cvt_pk_bf16_f32 v5, v6, v7
	v_cvt_pk_bf16_f32 v6, v0, v1
	v_cvt_pk_bf16_f32 v7, v2, v3
	s_nop 1
	v_permlane32_swap_b32_e32 v12, v14
	v_permlane32_swap_b32_e32 v13, v15
	v_permlane32_swap_b32_e32 v4, v6
	v_permlane32_swap_b32_e32 v5, v7
	s_nop 1
	v_permlane16_swap_b32_e32 v12, v14
	v_permlane16_swap_b32_e32 v13, v15
	v_permlane16_swap_b32_e32 v4, v6
	v_permlane16_swap_b32_e32 v5, v7
	global_store_dwordx4 v129, v[12:15], s[62:63]
	global_store_dwordx4 v129, v[4:7], s[62:63] offset:256
	s_branch .LBB0_200
; __device__ __forceinline__ void phaseA(const Params& p, int layer) {
;     ...
; #pragma unroll
;       for (int ai = 0; ai < 2; ai++)
; #pragma unroll
;         for (int m = 0; m < 4; m++) {
;           __builtin_amdgcn_sched_barrier(0);
;           const int tok = brow + ai * 128 + wr * 64 + m * 16 + fr_o;
; #pragma unroll
;           for (int bj = 0; bj < 2; bj++)
; #pragma unroll
;             for (int n = 0; n < 2; n++) {
;               const int cb = bcol + bj * 128 + wc * 32 + n * 16;
;               f32x4 v = acc[ai][bj][m][n];
;               if (n == 0 && (wc & 1) == 0 && ((cb >= C_ATQ && cb < C_ATV) || (cb >= C_IDQ && cb < C_IDW))) {
;                 f32x4 cs = *(const f32x4*)(p.CS + (size_t)tok * 16 + 4 * (fq & 1));
;                 f32x4 sn = *(const f32x4*)(p.CS + (size_t)tok * 16 + 8 + 4 * (fq & 1));
; #pragma unroll
;                 for (int e = 0; e < 4; e++) {
;                   float o = __shfl_xor(v[e], 32);
;                   v[e] = (fq < 2) ? (v[e] * cs[e] - o * sn[e]) : (v[e] * cs[e] + o * sn[e]);
;                 }
;               }
;               const int nn = cb + fq * 4;
;               if (nn < 5716) {
;                 const int dn = nn + (nn >= 2628 ? 12 : 0);
;                 uint2 pv = make_uint2(pk2(v[0], v[1]), pk2(v[2], v[3]));
;                 *(uint2*)(p.P + (size_t)tok * PW + dn) = pv;
.Lepa_fast12:
	v_readlane_b32 s62, v253, 13
	v_readlane_b32 s63, v253, 14
	v_mul_u32_u24_e32 v128, 0x2d00, v154
	v_lshl_add_u32 v129, v130, 1, s20
	v_lshl_add_u32 v128, v129, 1, v128
	v_add_u32_e32 v128, 24, v128
	v_cvt_pk_bf16_f32 v124, v124, v125
	v_cvt_pk_bf16_f32 v125, v126, v127
	v_cvt_pk_bf16_f32 v126, v120, v121
	v_cvt_pk_bf16_f32 v127, v122, v123
	v_cvt_pk_bf16_f32 v116, v116, v117
	v_cvt_pk_bf16_f32 v117, v118, v119
	v_cvt_pk_bf16_f32 v118, v112, v113
	v_cvt_pk_bf16_f32 v119, v114, v115
	s_nop 1
	v_permlane32_swap_b32_e32 v124, v126
	v_permlane32_swap_b32_e32 v125, v127
	v_permlane32_swap_b32_e32 v116, v118
	v_permlane32_swap_b32_e32 v117, v119
	s_nop 1
	v_permlane16_swap_b32_e32 v124, v126
	v_permlane16_swap_b32_e32 v125, v127
	v_permlane16_swap_b32_e32 v116, v118
	v_permlane16_swap_b32_e32 v117, v119
	global_store_dwordx4 v128, v[124:127], s[62:63]
	global_store_dwordx4 v128, v[116:119], s[62:63] offset:256
	v_add_u32_e32 v129, 0x2d000, v128
	v_cvt_pk_bf16_f32 v108, v108, v109
	v_cvt_pk_bf16_f32 v109, v110, v111
	v_cvt_pk_bf16_f32 v110, v104, v105
	v_cvt_pk_bf16_f32 v111, v106, v107
	v_cvt_pk_bf16_f32 v100, v100, v101
	v_cvt_pk_bf16_f32 v101, v102, v103
	v_cvt_pk_bf16_f32 v102, v96, v97
	v_cvt_pk_bf16_f32 v103, v98, v99
	s_nop 1
	v_permlane32_swap_b32_e32 v108, v110
	v_permlane32_swap_b32_e32 v109, v111
	v_permlane32_swap_b32_e32 v100, v102
	v_permlane32_swap_b32_e32 v101, v103
	s_nop 1
	v_permlane16_swap_b32_e32 v108, v110
	v_permlane16_swap_b32_e32 v109, v111
	v_permlane16_swap_b32_e32 v100, v102
	v_permlane16_swap_b32_e32 v101, v103
	global_store_dwordx4 v129, v[108:111], s[62:63]
	global_store_dwordx4 v129, v[100:103], s[62:63] offset:256
	v_add_u32_e32 v129, 0x5a000, v128
	v_cvt_pk_bf16_f32 v92, v92, v93
	v_cvt_pk_bf16_f32 v93, v94, v95
	v_cvt_pk_bf16_f32 v94, v88, v89
	v_cvt_pk_bf16_f32 v95, v90, v91
	v_cvt_pk_bf16_f32 v84, v84, v85
	v_cvt_pk_bf16_f32 v85, v86, v87
	v_cvt_pk_bf16_f32 v86, v80, v81
	v_cvt_pk_bf16_f32 v87, v82, v83
	s_nop 1
	v_permlane32_swap_b32_e32 v92, v94
	v_permlane32_swap_b32_e32 v93, v95
	v_permlane32_swap_b32_e32 v84, v86
	v_permlane32_swap_b32_e32 v85, v87
	s_nop 1
	v_permlane16_swap_b32_e32 v92, v94
	v_permlane16_swap_b32_e32 v93, v95
	v_permlane16_swap_b32_e32 v84, v86
	v_permlane16_swap_b32_e32 v85, v87
	global_store_dwordx4 v129, v[92:95], s[62:63]
	global_store_dwordx4 v129, v[84:87], s[62:63] offset:256
	v_add_u32_e32 v129, 0x87000, v128
	v_cvt_pk_bf16_f32 v76, v76, v77
	v_cvt_pk_bf16_f32 v77, v78, v79
	v_cvt_pk_bf16_f32 v78, v72, v73
	v_cvt_pk_bf16_f32 v79, v74, v75
	v_cvt_pk_bf16_f32 v68, v68, v69
	v_cvt_pk_bf16_f32 v69, v70, v71
	v_cvt_pk_bf16_f32 v70, v64, v65
	v_cvt_pk_bf16_f32 v71, v66, v67
	s_nop 1
	v_permlane32_swap_b32_e32 v76, v78
	v_permlane32_swap_b32_e32 v77, v79
	v_permlane32_swap_b32_e32 v68, v70
	v_permlane32_swap_b32_e32 v69, v71
	s_nop 1
	v_permlane16_swap_b32_e32 v76, v78
	v_permlane16_swap_b32_e32 v77, v79
	v_permlane16_swap_b32_e32 v68, v70
	v_permlane16_swap_b32_e32 v69, v71
	global_store_dwordx4 v129, v[76:79], s[62:63]
	global_store_dwordx4 v129, v[68:71], s[62:63] offset:256
	v_add_u32_e32 v129, 0x168000, v128
	v_cvt_pk_bf16_f32 v60, v60, v61
	v_cvt_pk_bf16_f32 v61, v62, v63
	v_cvt_pk_bf16_f32 v62, v56, v57
	v_cvt_pk_bf16_f32 v63, v58, v59
	v_cvt_pk_bf16_f32 v52, v52, v53
	v_cvt_pk_bf16_f32 v53, v54, v55
	v_cvt_pk_bf16_f32 v54, v48, v49
	v_cvt_pk_bf16_f32 v55, v50, v51
	s_nop 1
	v_permlane32_swap_b32_e32 v60, v62
	v_permlane32_swap_b32_e32 v61, v63
	v_permlane32_swap_b32_e32 v52, v54
	v_permlane32_swap_b32_e32 v53, v55
	s_nop 1
	v_permlane16_swap_b32_e32 v60, v62
	v_permlane16_swap_b32_e32 v61, v63
	v_permlane16_swap_b32_e32 v52, v54
	v_permlane16_swap_b32_e32 v53, v55
	global_store_dwordx4 v129, v[60:63], s[62:63]
	global_store_dwordx4 v129, v[52:55], s[62:63] offset:256
	v_add_u32_e32 v129, 0x195000, v128
	v_cvt_pk_bf16_f32 v44, v44, v45
	v_cvt_pk_bf16_f32 v45, v46, v47
	v_cvt_pk_bf16_f32 v46, v40, v41
	v_cvt_pk_bf16_f32 v47, v42, v43
	v_cvt_pk_bf16_f32 v36, v36, v37
	v_cvt_pk_bf16_f32 v37, v38, v39
	v_cvt_pk_bf16_f32 v38, v32, v33
	v_cvt_pk_bf16_f32 v39, v34, v35
	s_nop 1
	v_permlane32_swap_b32_e32 v44, v46
	v_permlane32_swap_b32_e32 v45, v47
	v_permlane32_swap_b32_e32 v36, v38
	v_permlane32_swap_b32_e32 v37, v39
	s_nop 1
	v_permlane16_swap_b32_e32 v44, v46
	v_permlane16_swap_b32_e32 v45, v47
	v_permlane16_swap_b32_e32 v36, v38
	v_permlane16_swap_b32_e32 v37, v39
	global_store_dwordx4 v129, v[44:47], s[62:63]
	global_store_dwordx4 v129, v[36:39], s[62:63] offset:256
	v_add_u32_e32 v129, 0x1c2000, v128
	v_cvt_pk_bf16_f32 v28, v28, v29
	v_cvt_pk_bf16_f32 v29, v30, v31
	v_cvt_pk_bf16_f32 v30, v24, v25
	v_cvt_pk_bf16_f32 v31, v26, v27
	v_cvt_pk_bf16_f32 v20, v20, v21
	v_cvt_pk_bf16_f32 v21, v22, v23
	v_cvt_pk_bf16_f32 v22, v16, v17
	v_cvt_pk_bf16_f32 v23, v18, v19
	s_nop 1
	v_permlane32_swap_b32_e32 v28, v30
	v_permlane32_swap_b32_e32 v29, v31
	v_permlane32_swap_b32_e32 v20, v22
	v_permlane32_swap_b32_e32 v21, v23
	s_nop 1
	v_permlane16_swap_b32_e32 v28, v30
	v_permlane16_swap_b32_e32 v29, v31
	v_permlane16_swap_b32_e32 v20, v22
	v_permlane16_swap_b32_e32 v21, v23
	global_store_dwordx4 v129, v[28:31], s[62:63]
	global_store_dwordx4 v129, v[20:23], s[62:63] offset:256
	v_add_u32_e32 v129, 0x1ef000, v128
	v_cvt_pk_bf16_f32 v12, v12, v13
	v_cvt_pk_bf16_f32 v13, v14, v15
	v_cvt_pk_bf16_f32 v14, v8, v9
	v_cvt_pk_bf16_f32 v15, v10, v11
	v_cvt_pk_bf16_f32 v4, v4, v5
	v_cvt_pk_bf16_f32 v5, v6, v7
	v_cvt_pk_bf16_f32 v6, v0, v1
	v_cvt_pk_bf16_f32 v7, v2, v3
	s_nop 1
	v_permlane32_swap_b32_e32 v12, v14
	v_permlane32_swap_b32_e32 v13, v15
	v_permlane32_swap_b32_e32 v4, v6
	v_permlane32_swap_b32_e32 v5, v7
	s_nop 1
	v_permlane16_swap_b32_e32 v12, v14
	v_permlane16_swap_b32_e32 v13, v15
	v_permlane16_swap_b32_e32 v4, v6
	v_permlane16_swap_b32_e32 v5, v7
	global_store_dwordx4 v129, v[12:15], s[62:63]
	global_store_dwordx4 v129, v[4:7], s[62:63] offset:256
	s_branch .LBB0_200

; __device__ __forceinline__ void phaseA(const Params& p, int layer) {
;     ...
;               const int cb = bcol + bj * 128 + wc * 32 + n * 16;
;               f32x4 v = acc[ai][bj][m][n];
;               if (n == 0 && (wc & 1) == 0 && ((cb >= C_ATQ && cb < C_ATV) || (cb >= C_IDQ && cb < C_IDW))) {
;                 f32x4 cs = *(const f32x4*)(p.CS + (size_t)tok * 16 + 4 * (fq & 1));
;                 f32x4 sn = *(const f32x4*)(p.CS + (size_t)tok * 16 + 8 + 4 * (fq & 1));
; #pragma unroll
;                 for (int e = 0; e < 4; e++) {
;                   float o = __shfl_xor(v[e], 32);
;                   v[e] = (fq < 2) ? (v[e] * cs[e] - o * sn[e]) : (v[e] * cs[e] + o * sn[e]);
;                 }
;               }
;               const int nn = cb + fq * 4;
;               if (nn < 5716) {
;                 const int dn = nn + (nn >= 2628 ? 12 : 0);
.LBB0_280:
	v_mov_b32_e32 v128, v133
	s_add_i32 s0, s0, s34
	s_or_b32 s20, s16, s35
	v_add_u32_e32 v154, s0, v128
	s_cmpk_lt_u32 s16, 0x400
	s_cbranch_scc1 .Lepa_fast0
	s_sub_u32 s2, s16, 0x700
	s_cmpk_lt_u32 s2, 0x200
	s_cbranch_scc1 .Lepa_fast0
	s_sub_u32 s2, s16, 0xb00
	s_cmpk_lt_u32 s2, 0xb00
	s_cbranch_scc1 .Lepa_fast12
	v_ashrrev_i32_e32 v155, 31, v154
	v_cndmask_b32_e64 v129, 0, 1, s[14:15]
	v_cmp_ne_u32_e64 s[0:1], 1, v129
	s_andn2_b64 vcc, exec, s[14:15]
	v_lshlrev_b64 v[160:161], 6, v[154:155]
	s_cbranch_vccnz .LBB0_283
	s_add_i32 s2, s16, 0xfffffc00
	s_cmpk_gt_u32 s2, 0x27f
	s_cselect_b64 s[2:3], -1, 0
	s_add_i32 s6, s20, 0xfffff700
	s_cmpk_gt_u32 s6, 0x13f
	s_cselect_b64 s[6:7], -1, 0
	s_and_b64 s[2:3], s[2:3], s[6:7]
	s_and_b64 vcc, exec, s[2:3]
	s_cbranch_vccnz .LBB0_283
	v_lshl_add_u64 v[162:163], v[152:153], 0, v[160:161]
	global_load_dwordx4 v[156:159], v[162:163], off
	s_nop 0
	global_load_dwordx4 v[162:165], v[162:163], off offset:32
	v_and_b32_e32 v139, 64, v202
	v_xor_b32_e32 v129, 32, v202
	v_add_u32_e32 v139, 64, v139
	v_cmp_lt_i32_e32 vcc, v129, v139
	s_nop 1
	v_cndmask_b32_e32 v129, v202, v129, vcc
	v_lshlrev_b32_e32 v129, 2, v129
	ds_bpermute_b32 v166, v129, v124
	ds_bpermute_b32 v167, v129, v125
	s_waitcnt vmcnt(0) lgkmcnt(0)
	v_pk_mul_f32 v[162:163], v[162:163], v[166:167]
	ds_bpermute_b32 v166, v129, v126
	ds_bpermute_b32 v167, v129, v127
	v_cndmask_b32_e64 v163, v163, -v163, s[4:5]
	v_cndmask_b32_e64 v162, v162, -v162, s[4:5]
	v_pk_fma_f32 v[124:125], v[124:125], v[156:157], v[162:163]
	s_waitcnt lgkmcnt(0)
	v_pk_mul_f32 v[164:165], v[164:165], v[166:167]
	s_nop 0
	v_cndmask_b32_e64 v165, v165, -v165, s[4:5]
	v_cndmask_b32_e64 v164, v164, -v164, s[4:5]
	v_pk_fma_f32 v[126:127], v[126:127], v[158:159], v[164:165]

; __device__ __forceinline__ void dsa_wave(const Params& p, int rank, char* sm) {
;     ...
;   Tg[0] = Tg[1] = Tg[2] = Tg[3] = 0u; Tq = 0u; cntv = 0;
;   Tf[0] = Tf[1] = Tf[2] = Tf[3] = -__builtin_inff();
;   const int ntile = (l0 + 7) / 32 + 1;
;   const bf* kif = p.KIF + (size_t)b * 512 * 2048 + lane * 8;
;   bf16x8 bqA[4][4], bqB[4][4];
; #pragma unroll
;   for (int s = 0; s < 4; s++) {
;     const int ts = s < ntile ? s : ntile - 1;
; #pragma unroll
;     for (int ks = 0; ks < 4; ks++) bqA[s][ks] = *(const bf16x8*)(kif + (size_t)ts * 2048 + ks * 512);
;   }
;   const unsigned ltmask = (1u << r32) - 1u;
.LBB0_543:
	v_mov_b32_e32 v144, 0
	v_mov_b32_e32 v173, 0
	s_and_saveexec_b64 s[42:43], s[6:7]
	s_cbranch_execz .LBB0_1451
	v_mov_b32_e32 v216, 0
	v_mov_b32_e32 v218, 0
	v_mov_b32_e32 v220, 0
	v_mov_b32_e32 v222, 0
	v_mov_b32_e32 v217, 0xff800000
	v_mov_b32_e32 v219, 0xff800000
	v_mov_b32_e32 v221, 0xff800000
	v_mov_b32_e32 v223, 0xff800000
	v_mov_b32_e32 v144, 0
	v_mov_b32_e32 v173, 0
	v_mov_b32_e32 v128, 0
	v_mov_b32_e32 v129, 0
	v_mov_b32_e32 v130, 0
	v_mov_b32_e32 v131, 0
	s_not_b64 s[58:59], s[4:5]
	v_sub_u32_e32 v132, 0x3fff, v157
	v_lshlrev_b32_e32 v11, 4, v151
	v_add_u32_e32 v137, 0x1000, v214
	v_add_u32_e32 v138, 0x2000, v214
	v_add_u32_e32 v139, 0x3000, v214
	v_lshlrev_b32_e32 v224, 12, v155
	v_add_u32_e32 v224, s77, v224
	v_lshl_add_u32 v136, v151, 2, v224
	v_readfirstlane_b32 s61, v189
	v_readfirstlane_b32 s66, v150
	v_readfirstlane_b32 s62, v203
	v_readlane_b32 s64, v253, 22
	v_readlane_b32 s65, v253, 23
	s_bfe_u32 s62, s62, 0x10006
	s_lshl_b32 s62, s62, 21
	s_add_u32 s64, s64, s62
	s_addc_u32 s65, s65, 0
	s_mov_b32 s60, 0
	s_min_u32 s62, 0, s61
	s_lshl_b32 s62, s62, 12
	v_add_u32_e32 v14, s62, v11
	global_load_dwordx4 v[32:35], v14, s[64:65]
	global_load_dwordx4 v[36:39], v14, s[64:65] offset:1024
	global_load_dwordx4 v[40:43], v14, s[64:65] offset:2048
	global_load_dwordx4 v[44:47], v14, s[64:65] offset:3072
	s_min_u32 s62, 1, s61
	s_lshl_b32 s62, s62, 12
	v_add_u32_e32 v14, s62, v11
	global_load_dwordx4 v[48:51], v14, s[64:65]
	global_load_dwordx4 v[52:55], v14, s[64:65] offset:1024
	global_load_dwordx4 v[56:59], v14, s[64:65] offset:2048
	global_load_dwordx4 v[60:63], v14, s[64:65] offset:3072
	s_min_u32 s62, 2, s61
	s_lshl_b32 s62, s62, 12
	v_add_u32_e32 v14, s62, v11
	global_load_dwordx4 v[64:67], v14, s[64:65]
	global_load_dwordx4 v[68:71], v14, s[64:65] offset:1024
	global_load_dwordx4 v[72:75], v14, s[64:65] offset:2048
	global_load_dwordx4 v[76:79], v14, s[64:65] offset:3072
	s_waitcnt vmcnt(8)
	v_mfma_f32_32x32x16_bf16 v[96:111], v[24:27], v[32:35], 0
	v_mfma_f32_32x32x16_bf16 v[96:111], v[16:19], v[36:39], v[96:111]
	v_mfma_f32_32x32x16_bf16 v[96:111], v[20:23], v[40:43], v[96:111]
	v_mfma_f32_32x32x16_bf16 v[96:111], v[28:31], v[44:47], v[96:111]
.Lidx_loop:
.Lidx_tile0:
	s_add_u32 s62, s60, 3
	s_min_u32 s62, s62, s61
	s_lshl_b32 s62, s62, 12
	v_add_u32_e32 v14, s62, v11
	global_load_dwordx4 v[80:83], v14, s[64:65]
	global_load_dwordx4 v[84:87], v14, s[64:65] offset:1024
	global_load_dwordx4 v[88:91], v14, s[64:65] offset:2048
	global_load_dwordx4 v[92:95], v14, s[64:65] offset:3072
	v_max3_u32 v15, v128, v129, v130
	v_max_u32_e32 v15, v15, v131
	v_cmp_lt_u32_e32 vcc, s80, v15
	s_cbranch_vccnz .Lidx_compact0
.Lidx_resume0:
	s_waitcnt vmcnt(8)
	v_mfma_f32_32x32x16_bf16 v[112:127], v[24:27], v[48:51], 0
	v_mfma_f32_32x32x16_bf16 v[112:127], v[16:19], v[52:55], v[112:127]
	v_mfma_f32_32x32x16_bf16 v[112:127], v[20:23], v[56:59], v[112:127]
	v_mfma_f32_32x32x16_bf16 v[112:127], v[28:31], v[60:63], v[112:127]
	s_lshl_b32 s62, s60, 5
	v_subrev_u32_e32 v13, s62, v132
	s_add_u32 s63, s62, 31
	s_cmp_gt_u32 s63, s66
	s_cbranch_scc1 .Lidx_diag0
	v_max_i32_e32 v96, 0, v96
	v_max_i32_e32 v100, 0, v100
	v_max_i32_e32 v104, 0, v104
	v_max_i32_e32 v108, 0, v108
	v_max_i32_e32 v97, 0, v97
	v_max_i32_e32 v101, 0, v101
	v_max_i32_e32 v105, 0, v105
	v_max_i32_e32 v109, 0, v109
	v_mul_f32_e32 v96, v159, v96
	v_mul_f32_e32 v100, v177, v100
	v_mul_f32_e32 v104, v181, v104
	v_mul_f32_e32 v108, v185, v108
	v_max_i32_e32 v98, 0, v98
	v_max_i32_e32 v102, 0, v102
	v_max_i32_e32 v106, 0, v106
	v_max_i32_e32 v110, 0, v110
	v_fmac_f32_e32 v96, v97, v174
	v_fmac_f32_e32 v100, v101, v178
	v_fmac_f32_e32 v104, v105, v182
	v_fmac_f32_e32 v108, v109, v186
	v_max_i32_e32 v99, 0, v99
	v_max_i32_e32 v103, 0, v103
	v_max_i32_e32 v107, 0, v107
	v_max_i32_e32 v111, 0, v111
	v_fmac_f32_e32 v96, v98, v175
	v_fmac_f32_e32 v100, v102, v179
	v_fmac_f32_e32 v104, v106, v183
	v_fmac_f32_e32 v108, v110, v187
	v_fmac_f32_e32 v96, v99, v176
	v_fmac_f32_e32 v100, v103, v180
	v_fmac_f32_e32 v104, v107, v184
	v_fmac_f32_e32 v108, v111, v188
	v_add_f32_e32 v96, 0, v96
	v_add_f32_e32 v100, 0, v100
	v_add_f32_e32 v104, 0, v104
	v_add_f32_e32 v108, 0, v108
	v_ashrrev_i32_e32 v97, 31, v96
	v_ashrrev_i32_e32 v101, 31, v100
	v_ashrrev_i32_e32 v105, 31, v104
	v_ashrrev_i32_e32 v109, 31, v108
	v_bitop3_b32 v96, v97, v96, s81 bitop3:0x36
	v_bitop3_b32 v100, v101, v100, s81 bitop3:0x36
	v_bitop3_b32 v104, v105, v104, s81 bitop3:0x36
	v_bitop3_b32 v108, v109, v108, s81 bitop3:0x36
	v_and_or_b32 v96, v96, s82, v13
	v_and_or_b32 v100, v100, s82, v13
	v_and_or_b32 v104, v104, s82, v13
	v_and_or_b32 v108, v108, s82, v13
	v_cmp_ge_u32_e64 s[26:27], v96, v216
	v_cmp_ge_u32_e64 s[28:29], v100, v218
	v_cmp_ge_u32_e64 s[30:31], v104, v220
	v_cmp_ge_u32_e64 s[34:35], v108, v222
	s_mov_b64 exec, s[4:5]
	v_mbcnt_lo_u32_b32 v97, s26, v128
	v_mbcnt_lo_u32_b32 v101, s28, v129
	v_mbcnt_lo_u32_b32 v105, s30, v130
	v_mbcnt_lo_u32_b32 v109, s34, v131
	v_bcnt_u32_b32 v128, s26, v128
	v_bcnt_u32_b32 v129, s28, v129
	v_bcnt_u32_b32 v130, s30, v130
	v_bcnt_u32_b32 v131, s34, v131
	s_mov_b64 exec, s[58:59]
	v_mbcnt_hi_u32_b32 v97, s27, v128
	v_mbcnt_hi_u32_b32 v101, s29, v129
	v_mbcnt_hi_u32_b32 v105, s31, v130
	v_mbcnt_hi_u32_b32 v109, s35, v131
	v_bcnt_u32_b32 v128, s27, v128
	v_bcnt_u32_b32 v129, s29, v129
	v_bcnt_u32_b32 v130, s31, v130
	v_bcnt_u32_b32 v131, s35, v131
	s_mov_b64 exec, -1
	v_lshl_add_u32 v97, v97, 2, v214
	v_lshl_add_u32 v101, v101, 2, v137
	v_lshl_add_u32 v105, v105, 2, v138
	v_lshl_add_u32 v109, v109, 2, v139
	s_mov_b64 exec, s[26:27]
	ds_write_b32 v97, v96
	s_mov_b64 exec, s[28:29]
	ds_write_b32 v101, v100
	s_mov_b64 exec, s[30:31]
	ds_write_b32 v105, v104
	s_mov_b64 exec, s[34:35]
	ds_write_b32 v109, v108
	s_mov_b64 exec, -1

.Lidx_tile1:
	s_add_u32 s62, s60, 3
	s_min_u32 s62, s62, s61
	s_lshl_b32 s62, s62, 12
	v_add_u32_e32 v14, s62, v11
	global_load_dwordx4 v[32:35], v14, s[64:65]
	global_load_dwordx4 v[36:39], v14, s[64:65] offset:1024
	global_load_dwordx4 v[40:43], v14, s[64:65] offset:2048
	global_load_dwordx4 v[44:47], v14, s[64:65] offset:3072
	v_max3_u32 v15, v128, v129, v130
	v_max_u32_e32 v15, v15, v131
	v_cmp_lt_u32_e32 vcc, s80, v15
	s_cbranch_vccnz .Lidx_compact1
.Lidx_resume1:
	s_waitcnt vmcnt(8)
	v_mfma_f32_32x32x16_bf16 v[96:111], v[24:27], v[64:67], 0
	v_mfma_f32_32x32x16_bf16 v[96:111], v[16:19], v[68:71], v[96:111]
	v_mfma_f32_32x32x16_bf16 v[96:111], v[20:23], v[72:75], v[96:111]
	v_mfma_f32_32x32x16_bf16 v[96:111], v[28:31], v[76:79], v[96:111]
	s_lshl_b32 s62, s60, 5
	v_subrev_u32_e32 v13, s62, v132
	s_add_u32 s63, s62, 31
	s_cmp_gt_u32 s63, s66
	s_cbranch_scc1 .Lidx_diag1
	v_max_i32_e32 v112, 0, v112
	v_max_i32_e32 v116, 0, v116
	v_max_i32_e32 v120, 0, v120
	v_max_i32_e32 v124, 0, v124
	v_max_i32_e32 v113, 0, v113
	v_max_i32_e32 v117, 0, v117
	v_max_i32_e32 v121, 0, v121
	v_max_i32_e32 v125, 0, v125
	v_mul_f32_e32 v112, v159, v112
	v_mul_f32_e32 v116, v177, v116
	v_mul_f32_e32 v120, v181, v120
	v_mul_f32_e32 v124, v185, v124
	v_max_i32_e32 v114, 0, v114
	v_max_i32_e32 v118, 0, v118
	v_max_i32_e32 v122, 0, v122
	v_max_i32_e32 v126, 0, v126
	v_fmac_f32_e32 v112, v113, v174
	v_fmac_f32_e32 v116, v117, v178
	v_fmac_f32_e32 v120, v121, v182
	v_fmac_f32_e32 v124, v125, v186
	v_max_i32_e32 v115, 0, v115
	v_max_i32_e32 v119, 0, v119
	v_max_i32_e32 v123, 0, v123
	v_max_i32_e32 v127, 0, v127
	v_fmac_f32_e32 v112, v114, v175
	v_fmac_f32_e32 v116, v118, v179
	v_fmac_f32_e32 v120, v122, v183
	v_fmac_f32_e32 v124, v126, v187
	v_fmac_f32_e32 v112, v115, v176
	v_fmac_f32_e32 v116, v119, v180
	v_fmac_f32_e32 v120, v123, v184
	v_fmac_f32_e32 v124, v127, v188
	v_add_f32_e32 v112, 0, v112
	v_add_f32_e32 v116, 0, v116
	v_add_f32_e32 v120, 0, v120
	v_add_f32_e32 v124, 0, v124
	v_ashrrev_i32_e32 v113, 31, v112
	v_ashrrev_i32_e32 v117, 31, v116
	v_ashrrev_i32_e32 v121, 31, v120
	v_ashrrev_i32_e32 v125, 31, v124
	v_bitop3_b32 v112, v113, v112, s81 bitop3:0x36
	v_bitop3_b32 v116, v117, v116, s81 bitop3:0x36
	v_bitop3_b32 v120, v121, v120, s81 bitop3:0x36
	v_bitop3_b32 v124, v125, v124, s81 bitop3:0x36
	v_and_or_b32 v112, v112, s82, v13
	v_and_or_b32 v116, v116, s82, v13
	v_and_or_b32 v120, v120, s82, v13
	v_and_or_b32 v124, v124, s82, v13
	v_cmp_ge_u32_e64 s[26:27], v112, v216
	v_cmp_ge_u32_e64 s[28:29], v116, v218
	v_cmp_ge_u32_e64 s[30:31], v120, v220
	v_cmp_ge_u32_e64 s[34:35], v124, v222
	s_mov_b64 exec, s[4:5]
	v_mbcnt_lo_u32_b32 v113, s26, v128
	v_mbcnt_lo_u32_b32 v117, s28, v129
	v_mbcnt_lo_u32_b32 v121, s30, v130
	v_mbcnt_lo_u32_b32 v125, s34, v131
	v_bcnt_u32_b32 v128, s26, v128
	v_bcnt_u32_b32 v129, s28, v129
	v_bcnt_u32_b32 v130, s30, v130
	v_bcnt_u32_b32 v131, s34, v131
	s_mov_b64 exec, s[58:59]
	v_mbcnt_hi_u32_b32 v113, s27, v128
	v_mbcnt_hi_u32_b32 v117, s29, v129
	v_mbcnt_hi_u32_b32 v121, s31, v130
	v_mbcnt_hi_u32_b32 v125, s35, v131
	v_bcnt_u32_b32 v128, s27, v128
	v_bcnt_u32_b32 v129, s29, v129
	v_bcnt_u32_b32 v130, s31, v130
	v_bcnt_u32_b32 v131, s35, v131
	s_mov_b64 exec, -1
	v_lshl_add_u32 v113, v113, 2, v214
	v_lshl_add_u32 v117, v117, 2, v137
	v_lshl_add_u32 v121, v121, 2, v138
	v_lshl_add_u32 v125, v125, 2, v139
	s_mov_b64 exec, s[26:27]
	ds_write_b32 v113, v112
	s_mov_b64 exec, s[28:29]
	ds_write_b32 v117, v116
	s_mov_b64 exec, s[30:31]
	ds_write_b32 v121, v120
	s_mov_b64 exec, s[34:35]
	ds_write_b32 v125, v124
	s_mov_b64 exec, -1

.Lidx_tile2:
	s_add_u32 s62, s60, 3
	s_min_u32 s62, s62, s61
	s_lshl_b32 s62, s62, 12
	v_add_u32_e32 v14, s62, v11
	global_load_dwordx4 v[48:51], v14, s[64:65]
	global_load_dwordx4 v[52:55], v14, s[64:65] offset:1024
	global_load_dwordx4 v[56:59], v14, s[64:65] offset:2048
	global_load_dwordx4 v[60:63], v14, s[64:65] offset:3072
	v_max3_u32 v15, v128, v129, v130
	v_max_u32_e32 v15, v15, v131
	v_cmp_lt_u32_e32 vcc, s80, v15
	s_cbranch_vccnz .Lidx_compact2
.Lidx_resume2:
	s_waitcnt vmcnt(8)
	v_mfma_f32_32x32x16_bf16 v[112:127], v[24:27], v[80:83], 0
	v_mfma_f32_32x32x16_bf16 v[112:127], v[16:19], v[84:87], v[112:127]
	v_mfma_f32_32x32x16_bf16 v[112:127], v[20:23], v[88:91], v[112:127]
	v_mfma_f32_32x32x16_bf16 v[112:127], v[28:31], v[92:95], v[112:127]
	s_lshl_b32 s62, s60, 5
	v_subrev_u32_e32 v13, s62, v132
	s_add_u32 s63, s62, 31
	s_cmp_gt_u32 s63, s66
	s_cbranch_scc1 .Lidx_diag2
	v_max_i32_e32 v96, 0, v96
	v_max_i32_e32 v100, 0, v100
	v_max_i32_e32 v104, 0, v104
	v_max_i32_e32 v108, 0, v108
	v_max_i32_e32 v97, 0, v97
	v_max_i32_e32 v101, 0, v101
	v_max_i32_e32 v105, 0, v105
	v_max_i32_e32 v109, 0, v109
	v_mul_f32_e32 v96, v159, v96
	v_mul_f32_e32 v100, v177, v100
	v_mul_f32_e32 v104, v181, v104
	v_mul_f32_e32 v108, v185, v108
	v_max_i32_e32 v98, 0, v98
	v_max_i32_e32 v102, 0, v102
	v_max_i32_e32 v106, 0, v106
	v_max_i32_e32 v110, 0, v110
	v_fmac_f32_e32 v96, v97, v174
	v_fmac_f32_e32 v100, v101, v178
	v_fmac_f32_e32 v104, v105, v182
	v_fmac_f32_e32 v108, v109, v186
	v_max_i32_e32 v99, 0, v99
	v_max_i32_e32 v103, 0, v103
	v_max_i32_e32 v107, 0, v107
	v_max_i32_e32 v111, 0, v111
	v_fmac_f32_e32 v96, v98, v175
	v_fmac_f32_e32 v100, v102, v179
	v_fmac_f32_e32 v104, v106, v183
	v_fmac_f32_e32 v108, v110, v187
	v_fmac_f32_e32 v96, v99, v176
	v_fmac_f32_e32 v100, v103, v180
	v_fmac_f32_e32 v104, v107, v184
	v_fmac_f32_e32 v108, v111, v188
	v_add_f32_e32 v96, 0, v96
	v_add_f32_e32 v100, 0, v100
	v_add_f32_e32 v104, 0, v104
	v_add_f32_e32 v108, 0, v108
	v_ashrrev_i32_e32 v97, 31, v96
	v_ashrrev_i32_e32 v101, 31, v100
	v_ashrrev_i32_e32 v105, 31, v104
	v_ashrrev_i32_e32 v109, 31, v108
	v_bitop3_b32 v96, v97, v96, s81 bitop3:0x36
	v_bitop3_b32 v100, v101, v100, s81 bitop3:0x36
	v_bitop3_b32 v104, v105, v104, s81 bitop3:0x36
	v_bitop3_b32 v108, v109, v108, s81 bitop3:0x36
	v_and_or_b32 v96, v96, s82, v13
	v_and_or_b32 v100, v100, s82, v13
	v_and_or_b32 v104, v104, s82, v13
	v_and_or_b32 v108, v108, s82, v13
	v_cmp_ge_u32_e64 s[26:27], v96, v216
	v_cmp_ge_u32_e64 s[28:29], v100, v218
	v_cmp_ge_u32_e64 s[30:31], v104, v220
	v_cmp_ge_u32_e64 s[34:35], v108, v222
	s_mov_b64 exec, s[4:5]
	v_mbcnt_lo_u32_b32 v97, s26, v128
	v_mbcnt_lo_u32_b32 v101, s28, v129
	v_mbcnt_lo_u32_b32 v105, s30, v130
	v_mbcnt_lo_u32_b32 v109, s34, v131
	v_bcnt_u32_b32 v128, s26, v128
	v_bcnt_u32_b32 v129, s28, v129
	v_bcnt_u32_b32 v130, s30, v130
	v_bcnt_u32_b32 v131, s34, v131
	s_mov_b64 exec, s[58:59]
	v_mbcnt_hi_u32_b32 v97, s27, v128
	v_mbcnt_hi_u32_b32 v101, s29, v129
	v_mbcnt_hi_u32_b32 v105, s31, v130
	v_mbcnt_hi_u32_b32 v109, s35, v131
	v_bcnt_u32_b32 v128, s27, v128
	v_bcnt_u32_b32 v129, s29, v129
	v_bcnt_u32_b32 v130, s31, v130
	v_bcnt_u32_b32 v131, s35, v131
	s_mov_b64 exec, -1
	v_lshl_add_u32 v97, v97, 2, v214
	v_lshl_add_u32 v101, v101, 2, v137
	v_lshl_add_u32 v105, v105, 2, v138
	v_lshl_add_u32 v109, v109, 2, v139
	s_mov_b64 exec, s[26:27]
	ds_write_b32 v97, v96
	s_mov_b64 exec, s[28:29]
	ds_write_b32 v101, v100
	s_mov_b64 exec, s[30:31]
	ds_write_b32 v105, v104
	s_mov_b64 exec, s[34:35]
	ds_write_b32 v109, v108
	s_mov_b64 exec, -1

.Lidx_tile3:
	s_add_u32 s62, s60, 3
	s_min_u32 s62, s62, s61
	s_lshl_b32 s62, s62, 12
	v_add_u32_e32 v14, s62, v11
	global_load_dwordx4 v[64:67], v14, s[64:65]
	global_load_dwordx4 v[68:71], v14, s[64:65] offset:1024
	global_load_dwordx4 v[72:75], v14, s[64:65] offset:2048
	global_load_dwordx4 v[76:79], v14, s[64:65] offset:3072
	v_max3_u32 v15, v128, v129, v130
	v_max_u32_e32 v15, v15, v131
	v_cmp_lt_u32_e32 vcc, s80, v15
	s_cbranch_vccnz .Lidx_compact3
.Lidx_resume3:
	s_waitcnt vmcnt(8)
	v_mfma_f32_32x32x16_bf16 v[96:111], v[24:27], v[32:35], 0
	v_mfma_f32_32x32x16_bf16 v[96:111], v[16:19], v[36:39], v[96:111]
	v_mfma_f32_32x32x16_bf16 v[96:111], v[20:23], v[40:43], v[96:111]
	v_mfma_f32_32x32x16_bf16 v[96:111], v[28:31], v[44:47], v[96:111]
	s_lshl_b32 s62, s60, 5
	v_subrev_u32_e32 v13, s62, v132
	s_add_u32 s63, s62, 31
	s_cmp_gt_u32 s63, s66
	s_cbranch_scc1 .Lidx_diag3
	v_max_i32_e32 v112, 0, v112
	v_max_i32_e32 v116, 0, v116
	v_max_i32_e32 v120, 0, v120
	v_max_i32_e32 v124, 0, v124
	v_max_i32_e32 v113, 0, v113
	v_max_i32_e32 v117, 0, v117
	v_max_i32_e32 v121, 0, v121
	v_max_i32_e32 v125, 0, v125
	v_mul_f32_e32 v112, v159, v112
	v_mul_f32_e32 v116, v177, v116
	v_mul_f32_e32 v120, v181, v120
	v_mul_f32_e32 v124, v185, v124
	v_max_i32_e32 v114, 0, v114
	v_max_i32_e32 v118, 0, v118
	v_max_i32_e32 v122, 0, v122
	v_max_i32_e32 v126, 0, v126
	v_fmac_f32_e32 v112, v113, v174
	v_fmac_f32_e32 v116, v117, v178
	v_fmac_f32_e32 v120, v121, v182
	v_fmac_f32_e32 v124, v125, v186
	v_max_i32_e32 v115, 0, v115
	v_max_i32_e32 v119, 0, v119
	v_max_i32_e32 v123, 0, v123
	v_max_i32_e32 v127, 0, v127
	v_fmac_f32_e32 v112, v114, v175
	v_fmac_f32_e32 v116, v118, v179
	v_fmac_f32_e32 v120, v122, v183
	v_fmac_f32_e32 v124, v126, v187
	v_fmac_f32_e32 v112, v115, v176
	v_fmac_f32_e32 v116, v119, v180
	v_fmac_f32_e32 v120, v123, v184
	v_fmac_f32_e32 v124, v127, v188
	v_add_f32_e32 v112, 0, v112
	v_add_f32_e32 v116, 0, v116
	v_add_f32_e32 v120, 0, v120
	v_add_f32_e32 v124, 0, v124
	v_ashrrev_i32_e32 v113, 31, v112
	v_ashrrev_i32_e32 v117, 31, v116
	v_ashrrev_i32_e32 v121, 31, v120
	v_ashrrev_i32_e32 v125, 31, v124
	v_bitop3_b32 v112, v113, v112, s81 bitop3:0x36
	v_bitop3_b32 v116, v117, v116, s81 bitop3:0x36
	v_bitop3_b32 v120, v121, v120, s81 bitop3:0x36
	v_bitop3_b32 v124, v125, v124, s81 bitop3:0x36
	v_and_or_b32 v112, v112, s82, v13
	v_and_or_b32 v116, v116, s82, v13
	v_and_or_b32 v120, v120, s82, v13
	v_and_or_b32 v124, v124, s82, v13
	v_cmp_ge_u32_e64 s[26:27], v112, v216
	v_cmp_ge_u32_e64 s[28:29], v116, v218
	v_cmp_ge_u32_e64 s[30:31], v120, v220
	v_cmp_ge_u32_e64 s[34:35], v124, v222
	s_mov_b64 exec, s[4:5]
	v_mbcnt_lo_u32_b32 v113, s26, v128
	v_mbcnt_lo_u32_b32 v117, s28, v129
	v_mbcnt_lo_u32_b32 v121, s30, v130
	v_mbcnt_lo_u32_b32 v125, s34, v131
	v_bcnt_u32_b32 v128, s26, v128
	v_bcnt_u32_b32 v129, s28, v129
	v_bcnt_u32_b32 v130, s30, v130
	v_bcnt_u32_b32 v131, s34, v131
	s_mov_b64 exec, s[58:59]
	v_mbcnt_hi_u32_b32 v113, s27, v128
	v_mbcnt_hi_u32_b32 v117, s29, v129
	v_mbcnt_hi_u32_b32 v121, s31, v130
	v_mbcnt_hi_u32_b32 v125, s35, v131
	v_bcnt_u32_b32 v128, s27, v128
	v_bcnt_u32_b32 v129, s29, v129
	v_bcnt_u32_b32 v130, s31, v130
	v_bcnt_u32_b32 v131, s35, v131
	s_mov_b64 exec, -1
	v_lshl_add_u32 v113, v113, 2, v214
	v_lshl_add_u32 v117, v117, 2, v137
	v_lshl_add_u32 v121, v121, 2, v138
	v_lshl_add_u32 v125, v125, 2, v139
	s_mov_b64 exec, s[26:27]
	ds_write_b32 v113, v112
	s_mov_b64 exec, s[28:29]
	ds_write_b32 v117, v116
	s_mov_b64 exec, s[30:31]
	ds_write_b32 v121, v120
	s_mov_b64 exec, s[34:35]
	ds_write_b32 v125, v124
	s_mov_b64 exec, -1

.Lidx_diag0:
	v_add_u32_e32 v215, s62, v157
	v_max_i32_e32 v96, 0, v96
	v_max_i32_e32 v100, 0, v100
	v_max_i32_e32 v104, 0, v104
	v_max_i32_e32 v108, 0, v108
	v_max_i32_e32 v97, 0, v97
	v_max_i32_e32 v101, 0, v101
	v_max_i32_e32 v105, 0, v105
	v_max_i32_e32 v109, 0, v109
	v_mul_f32_e32 v96, v159, v96
	v_mul_f32_e32 v100, v177, v100
	v_mul_f32_e32 v104, v181, v104
	v_mul_f32_e32 v108, v185, v108
	v_max_i32_e32 v98, 0, v98
	v_max_i32_e32 v102, 0, v102
	v_max_i32_e32 v106, 0, v106
	v_max_i32_e32 v110, 0, v110
	v_fmac_f32_e32 v96, v97, v174
	v_fmac_f32_e32 v100, v101, v178
	v_fmac_f32_e32 v104, v105, v182
	v_fmac_f32_e32 v108, v109, v186
	v_max_i32_e32 v99, 0, v99
	v_max_i32_e32 v103, 0, v103
	v_max_i32_e32 v107, 0, v107
	v_max_i32_e32 v111, 0, v111
	v_fmac_f32_e32 v96, v98, v175
	v_fmac_f32_e32 v100, v102, v179
	v_fmac_f32_e32 v104, v106, v183
	v_fmac_f32_e32 v108, v110, v187
	v_fmac_f32_e32 v96, v99, v176
	v_fmac_f32_e32 v100, v103, v180
	v_fmac_f32_e32 v104, v107, v184
	v_fmac_f32_e32 v108, v111, v188
	v_add_f32_e32 v96, 0, v96
	v_add_f32_e32 v100, 0, v100
	v_add_f32_e32 v104, 0, v104
	v_add_f32_e32 v108, 0, v108
	v_ashrrev_i32_e32 v97, 31, v96
	v_ashrrev_i32_e32 v101, 31, v100
	v_ashrrev_i32_e32 v105, 31, v104
	v_ashrrev_i32_e32 v109, 31, v108
	v_bitop3_b32 v96, v97, v96, s81 bitop3:0x36
	v_bitop3_b32 v100, v101, v100, s81 bitop3:0x36
	v_bitop3_b32 v104, v105, v104, s81 bitop3:0x36
	v_bitop3_b32 v108, v109, v108, s81 bitop3:0x36
	v_and_or_b32 v96, v96, s82, v13
	v_and_or_b32 v100, v100, s82, v13
	v_and_or_b32 v104, v104, s82, v13
	v_and_or_b32 v108, v108, s82, v13
	v_cmp_ge_u32_e64 s[26:27], v96, v216
	v_cmp_ge_u32_e64 s[28:29], v100, v218
	v_cmp_ge_u32_e64 s[30:31], v104, v220
	v_cmp_ge_u32_e64 s[34:35], v108, v222
	v_cmp_le_i32_e64 s[36:37], v215, v152
	v_cmp_le_i32_e64 s[38:39], v215, v154
	v_cmp_le_i32_e64 s[40:41], v215, v156
	v_cmp_le_i32_e64 s[2:3], v215, v158
	s_and_b64 s[26:27], s[26:27], s[36:37]
	s_and_b64 s[28:29], s[28:29], s[38:39]
	s_and_b64 s[30:31], s[30:31], s[40:41]
	s_and_b64 s[34:35], s[34:35], s[2:3]
	s_mov_b64 exec, s[4:5]
	v_mbcnt_lo_u32_b32 v97, s26, v128
	v_mbcnt_lo_u32_b32 v101, s28, v129
	v_mbcnt_lo_u32_b32 v105, s30, v130
	v_mbcnt_lo_u32_b32 v109, s34, v131
	v_bcnt_u32_b32 v128, s26, v128
	v_bcnt_u32_b32 v129, s28, v129
	v_bcnt_u32_b32 v130, s30, v130
	v_bcnt_u32_b32 v131, s34, v131
	s_mov_b64 exec, s[58:59]
	v_mbcnt_hi_u32_b32 v97, s27, v128
	v_mbcnt_hi_u32_b32 v101, s29, v129
	v_mbcnt_hi_u32_b32 v105, s31, v130
	v_mbcnt_hi_u32_b32 v109, s35, v131
	v_bcnt_u32_b32 v128, s27, v128
	v_bcnt_u32_b32 v129, s29, v129
	v_bcnt_u32_b32 v130, s31, v130
	v_bcnt_u32_b32 v131, s35, v131
	s_mov_b64 exec, -1
	v_lshl_add_u32 v97, v97, 2, v214
	v_lshl_add_u32 v101, v101, 2, v137
	v_lshl_add_u32 v105, v105, 2, v138
	v_lshl_add_u32 v109, v109, 2, v139
	s_mov_b64 exec, s[26:27]
	ds_write_b32 v97, v96
	s_mov_b64 exec, s[28:29]
	ds_write_b32 v101, v100
	s_mov_b64 exec, s[30:31]
	ds_write_b32 v105, v104
	s_mov_b64 exec, s[34:35]
	ds_write_b32 v109, v108
	s_mov_b64 exec, -1
	s_branch .Lidx_next0
.Lidx_diag1:
	v_add_u32_e32 v215, s62, v157
	v_max_i32_e32 v112, 0, v112
	v_max_i32_e32 v116, 0, v116
	v_max_i32_e32 v120, 0, v120
	v_max_i32_e32 v124, 0, v124
	v_max_i32_e32 v113, 0, v113
	v_max_i32_e32 v117, 0, v117
	v_max_i32_e32 v121, 0, v121
	v_max_i32_e32 v125, 0, v125
	v_mul_f32_e32 v112, v159, v112
	v_mul_f32_e32 v116, v177, v116
	v_mul_f32_e32 v120, v181, v120
	v_mul_f32_e32 v124, v185, v124
	v_max_i32_e32 v114, 0, v114
	v_max_i32_e32 v118, 0, v118
	v_max_i32_e32 v122, 0, v122
	v_max_i32_e32 v126, 0, v126
	v_fmac_f32_e32 v112, v113, v174
	v_fmac_f32_e32 v116, v117, v178
	v_fmac_f32_e32 v120, v121, v182
	v_fmac_f32_e32 v124, v125, v186
	v_max_i32_e32 v115, 0, v115
	v_max_i32_e32 v119, 0, v119
	v_max_i32_e32 v123, 0, v123
	v_max_i32_e32 v127, 0, v127
	v_fmac_f32_e32 v112, v114, v175
	v_fmac_f32_e32 v116, v118, v179
	v_fmac_f32_e32 v120, v122, v183
	v_fmac_f32_e32 v124, v126, v187
	v_fmac_f32_e32 v112, v115, v176
	v_fmac_f32_e32 v116, v119, v180
	v_fmac_f32_e32 v120, v123, v184
	v_fmac_f32_e32 v124, v127, v188
	v_add_f32_e32 v112, 0, v112
	v_add_f32_e32 v116, 0, v116
	v_add_f32_e32 v120, 0, v120
	v_add_f32_e32 v124, 0, v124
	v_ashrrev_i32_e32 v113, 31, v112
	v_ashrrev_i32_e32 v117, 31, v116
	v_ashrrev_i32_e32 v121, 31, v120
	v_ashrrev_i32_e32 v125, 31, v124
	v_bitop3_b32 v112, v113, v112, s81 bitop3:0x36
	v_bitop3_b32 v116, v117, v116, s81 bitop3:0x36
	v_bitop3_b32 v120, v121, v120, s81 bitop3:0x36
	v_bitop3_b32 v124, v125, v124, s81 bitop3:0x36
	v_and_or_b32 v112, v112, s82, v13
	v_and_or_b32 v116, v116, s82, v13
	v_and_or_b32 v120, v120, s82, v13
	v_and_or_b32 v124, v124, s82, v13
	v_cmp_ge_u32_e64 s[26:27], v112, v216
	v_cmp_ge_u32_e64 s[28:29], v116, v218
	v_cmp_ge_u32_e64 s[30:31], v120, v220
	v_cmp_ge_u32_e64 s[34:35], v124, v222
	v_cmp_le_i32_e64 s[36:37], v215, v152
	v_cmp_le_i32_e64 s[38:39], v215, v154
	v_cmp_le_i32_e64 s[40:41], v215, v156
	v_cmp_le_i32_e64 s[2:3], v215, v158
	s_and_b64 s[26:27], s[26:27], s[36:37]
	s_and_b64 s[28:29], s[28:29], s[38:39]
	s_and_b64 s[30:31], s[30:31], s[40:41]
	s_and_b64 s[34:35], s[34:35], s[2:3]
	s_mov_b64 exec, s[4:5]
	v_mbcnt_lo_u32_b32 v113, s26, v128
	v_mbcnt_lo_u32_b32 v117, s28, v129
	v_mbcnt_lo_u32_b32 v121, s30, v130
	v_mbcnt_lo_u32_b32 v125, s34, v131
	v_bcnt_u32_b32 v128, s26, v128
	v_bcnt_u32_b32 v129, s28, v129
	v_bcnt_u32_b32 v130, s30, v130
	v_bcnt_u32_b32 v131, s34, v131
	s_mov_b64 exec, s[58:59]
	v_mbcnt_hi_u32_b32 v113, s27, v128
	v_mbcnt_hi_u32_b32 v117, s29, v129
	v_mbcnt_hi_u32_b32 v121, s31, v130
	v_mbcnt_hi_u32_b32 v125, s35, v131
	v_bcnt_u32_b32 v128, s27, v128
	v_bcnt_u32_b32 v129, s29, v129
	v_bcnt_u32_b32 v130, s31, v130
	v_bcnt_u32_b32 v131, s35, v131
	s_mov_b64 exec, -1
	v_lshl_add_u32 v113, v113, 2, v214
	v_lshl_add_u32 v117, v117, 2, v137
	v_lshl_add_u32 v121, v121, 2, v138
	v_lshl_add_u32 v125, v125, 2, v139
	s_mov_b64 exec, s[26:27]
	ds_write_b32 v113, v112
	s_mov_b64 exec, s[28:29]
	ds_write_b32 v117, v116
	s_mov_b64 exec, s[30:31]
	ds_write_b32 v121, v120
	s_mov_b64 exec, s[34:35]
	ds_write_b32 v125, v124
	s_mov_b64 exec, -1
	s_branch .Lidx_next1

.Lidx_compact:
	v_readlane_b32 s52, v128, 0
	v_readlane_b32 s53, v128, 32
	v_readlane_b32 s54, v129, 0
	v_readlane_b32 s55, v129, 32
	v_readlane_b32 s56, v130, 0
	v_readlane_b32 s57, v130, 32
	v_readlane_b32 s26, v131, 0
	v_readlane_b32 s27, v131, 32
	v_mov_b32_e32 v173, 0
	v_writelane_b32 v173, s52, 0
	v_writelane_b32 v173, s53, 1
	v_writelane_b32 v173, s54, 2
	v_writelane_b32 v173, s55, 3
	v_writelane_b32 v173, s56, 4
	v_writelane_b32 v173, s57, 5
	v_writelane_b32 v173, s26, 6
	v_writelane_b32 v173, s27, 7
	v_cmp_lt_i32_e32 vcc, s80, v173
	s_and_b64 s[0:1], s[8:9], vcc
	s_branch .LBB0_549
.Lidx_done:
	v_readlane_b32 s52, v128, 0
	v_readlane_b32 s53, v128, 32
	v_readlane_b32 s54, v129, 0
	v_readlane_b32 s55, v129, 32
	v_readlane_b32 s56, v130, 0
	v_readlane_b32 s57, v130, 32
	v_readlane_b32 s26, v131, 0
	v_readlane_b32 s27, v131, 32
	v_mov_b32_e32 v173, 0
	v_writelane_b32 v173, s52, 0
	v_writelane_b32 v173, s53, 1
	v_writelane_b32 v173, s54, 2
	v_writelane_b32 v173, s55, 3
	v_writelane_b32 v173, s56, 4
	v_writelane_b32 v173, s57, 5
	v_writelane_b32 v173, s26, 6
	v_writelane_b32 v173, s27, 7
	s_branch .LBB0_1451

.LBB0_616:
	v_readlane_b32 s0, v144, 0
	v_readlane_b32 s1, v144, 1
	s_nop 0
	v_mov_b32_e32 v1, s0
	v_mov_b32_e32 v0, s1
	v_cndmask_b32_e64 v216, v0, v1, s[4:5]
	v_cmp_lt_i32_e32 vcc, -1, v216
	v_readlane_b32 s0, v144, 2
	v_readlane_b32 s1, v144, 3
	v_cndmask_b32_e64 v0, v207, -1, vcc
	v_bitop3_b32 v0, v0, v216, s82 bitop3:0x78
	v_cmp_ne_u32_e32 vcc, 0, v216
	v_mov_b32_e32 v1, s0
	v_readlane_b32 s0, v144, 4
	v_cndmask_b32_e32 v217, v208, v0, vcc
	v_mov_b32_e32 v0, s1
	v_cndmask_b32_e64 v218, v0, v1, s[4:5]
	v_cmp_lt_i32_e32 vcc, -1, v218
	v_readlane_b32 s1, v144, 5
	v_mov_b32_e32 v1, s0
	v_cndmask_b32_e64 v0, v207, -1, vcc
	v_bitop3_b32 v0, v0, v218, s82 bitop3:0x78
	v_cmp_ne_u32_e32 vcc, 0, v218
	v_readlane_b32 s0, v144, 6
	s_nop 0
	v_cndmask_b32_e32 v219, v208, v0, vcc
	v_mov_b32_e32 v0, s1
	v_cndmask_b32_e64 v220, v0, v1, s[4:5]
	v_cmp_lt_i32_e32 vcc, -1, v220
	v_readlane_b32 s1, v144, 7
	v_mov_b32_e32 v1, s0
	v_cndmask_b32_e64 v0, v207, -1, vcc
	v_bitop3_b32 v0, v0, v220, s82 bitop3:0x78
	v_cmp_ne_u32_e32 vcc, 0, v220
	s_nop 1
	v_cndmask_b32_e32 v221, v208, v0, vcc
	v_mov_b32_e32 v0, s1
	v_cndmask_b32_e64 v222, v0, v1, s[4:5]
	v_cmp_lt_i32_e32 vcc, -1, v222
	s_nop 1
	v_cndmask_b32_e64 v0, v207, -1, vcc
	v_bitop3_b32 v0, v0, v222, s82 bitop3:0x78
	v_cmp_ne_u32_e32 vcc, 0, v222
	s_nop 1
	v_cndmask_b32_e32 v223, v208, v0, vcc
	s_nop 1
	v_readlane_b32 s52, v173, 0
	v_readlane_b32 s53, v173, 1
	v_readlane_b32 s54, v173, 2
	v_readlane_b32 s55, v173, 3
	v_readlane_b32 s56, v173, 4
	v_readlane_b32 s57, v173, 5
	v_readlane_b32 s26, v173, 6
	v_readlane_b32 s27, v173, 7
	s_nop 1
	v_mov_b32_e32 v128, s52
	v_mov_b32_e32 v129, s54
	v_mov_b32_e32 v130, s56
	v_mov_b32_e32 v131, s26
	s_mov_b64 exec, s[58:59]
	v_mov_b32_e32 v128, s53
	v_mov_b32_e32 v129, s55
	v_mov_b32_e32 v130, s57
	v_mov_b32_e32 v131, s27
	s_mov_b64 exec, -1
	s_cmp_eq_u32 s67, 0
	s_cbranch_scc1 .Lidx_resume0
	s_cmp_eq_u32 s67, 1
	s_cbranch_scc1 .Lidx_resume1
	s_cmp_eq_u32 s67, 2
	s_cbranch_scc1 .Lidx_resume2
	s_branch .Lidx_resume3
